# helper stage math: 8 cvt + 4 packed-f32 ops replaced by 8 v_fma_mix_f32 reading the fp16 a/k operands directly (same f32 rounding), 4 fewer VALU per staged group
# speedup vs baseline: 1.0312x; 1.0009x over previous
.LBB0_182:
	s_min_u32 s4, s37, 0x1030
	s_lshl_b32 s4, s4, 2
	s_cmp_gt_u32 s37, 48
	s_cselect_b32 s5, 0xffffff3c, 60
	s_cselect_b32 s23, s10, s33
	s_cselect_b32 s37, s46, 0xfc
	s_add_i32 s44, s4, s5
	s_sub_i32 s37, s37, s44
	s_waitcnt vmcnt(38)
	s_and_b64 s[4:5], s[42:43], exec
	s_waitcnt vmcnt(36)
	v_fma_mix_f32 v188, v91, v2, v92 op_sel:[0,0,0] op_sel_hi:[1,0,0]
	v_fma_mix_f32 v189, v91, v3, v93 op_sel:[1,0,0] op_sel_hi:[1,0,0]
	v_fma_mix_f32 v190, v90, v0, v94 op_sel:[0,0,0] op_sel_hi:[1,0,0]
	v_fma_mix_f32 v191, v90, v1, v95 op_sel:[1,0,0] op_sel_hi:[1,0,0]
	v_fma_mix_f32 v192, v103, v188, 0 op_sel:[0,0,0] op_sel_hi:[1,0,0]
	v_fma_mix_f32 v193, v103, v189, 0 op_sel:[1,0,0] op_sel_hi:[1,0,0]
	v_fma_mix_f32 v194, v102, v190, 0 op_sel:[0,0,0] op_sel_hi:[1,0,0]
	v_fma_mix_f32 v195, v102, v191, 0 op_sel:[1,0,0] op_sel_hi:[1,0,0]
	s_cselect_b32 s4, s44, s37
	s_add_i32 s4, s4, s23
	s_ashr_i32 s5, s4, 31
	s_lshl_b64 s[4:5], s[4:5], 11
	v_add_u32_e32 v187, s4, v119
	v_pk_mul_f16 v123, v91, v35
	v_pk_mul_f16 v122, v90, v34
	v_cvt_pk_f16_f32 v125, v192, v193
	v_cvt_pk_f16_f32 v124, v194, v195
	ds_write_b128 v120, v[32:35] offset:21504
	ds_write_b128 v120, v[122:125] offset:22528
	s_waitcnt vmcnt(35)
	v_add_u32_e32 v185, v121, v186
	ds_write_b64 v185, v[100:101] offset:23552
	v_mov_b32_e32 v32, s22
	s_waitcnt lgkmcnt(0)
	ds_write_b32 v161, v32 offset:49152
	global_load_dwordx2 v[32:33], v187, s[74:75]
	global_load_dwordx2 v[90:91], v187, s[76:77]
	global_load_dwordx2 v[34:35], v187, s[78:79]
	global_load_dwordx2 v[102:103], v187, s[80:81]
	global_load_dwordx2 v[100:101], v187, s[82:83]
	s_nop 0
	s_andn2_b64 vcc, exec, s[90:91]
	s_mov_b32 s37, s22
	s_cbranch_vccz .LBB0_242

.LBB0_185:
	s_waitcnt vmcnt(38)
	s_waitcnt vmcnt(36)
	s_and_b32 s4, s37, 8
	s_mulk_i32 s4, 0xc00
	s_add_i32 s4, s4, 16
	s_or_b32 s23, s37, 1
	s_add_i32 s22, s37, 8
	s_cmpk_gt_u32 s37, 0x1037
	v_fma_mix_f32 v188, v36, v0, v94 op_sel:[0,0,0] op_sel_hi:[1,0,0]
	v_fma_mix_f32 v189, v36, v1, v95 op_sel:[1,0,0] op_sel_hi:[1,0,0]
	v_fma_mix_f32 v190, v37, v2, v92 op_sel:[0,0,0] op_sel_hi:[1,0,0]
	v_fma_mix_f32 v191, v37, v3, v93 op_sel:[1,0,0] op_sel_hi:[1,0,0]
	v_fma_mix_f32 v192, v44, v188, 0 op_sel:[0,0,0] op_sel_hi:[1,0,0]
	v_fma_mix_f32 v193, v44, v189, 0 op_sel:[1,0,0] op_sel_hi:[1,0,0]
	v_fma_mix_f32 v194, v45, v190, 0 op_sel:[0,0,0] op_sel_hi:[1,0,0]
	v_fma_mix_f32 v195, v45, v191, 0 op_sel:[1,0,0] op_sel_hi:[1,0,0]
	v_pk_mul_f16 v122, v36, v6
	v_cvt_pk_f16_f32 v124, v192, v193
	v_add_u32_e32 v36, s4, v113
	v_add_u32_e32 v121, s4, v111
	s_cselect_b64 s[90:91], -1, 0
	s_lshl_b32 s4, s22, 2
	s_cmpk_lt_u32 s37, 0x1038
	s_cselect_b32 s4, s4, 0x40fc
	s_add_i32 s5, s4, 0xffffff00
	s_min_u32 s44, s5, s4
	s_cmpk_gt_u32 s4, 0xff
	s_movk_i32 s4, 0x3fff
	s_cselect_b32 s4, s4, 0xff
	s_cselect_b32 s45, s10, s33
	s_sub_i32 s4, s4, s44
	s_add_i32 vcc_lo, s4, -3
	s_and_b64 s[4:5], s[42:43], exec
	s_cselect_b32 s4, s44, vcc_lo
	s_add_i32 s4, s4, s45
	s_ashr_i32 s5, s4, 31
	s_lshl_b64 s[4:5], s[4:5], 11
	v_add_u32_e32 v187, s4, v119
	v_add_u32_e32 v120, v36, v128
	v_pk_mul_f16 v123, v37, v7
	v_cvt_pk_f16_f32 v125, v194, v195
	ds_write_b128 v120, v[4:7]
	ds_write_b128 v120, v[122:125] offset:1024
	s_waitcnt vmcnt(35)
	v_add_u32_e32 v185, v121, v186
	ds_write_b64 v185, v[38:39] offset:2048
	v_mov_b32_e32 v4, s23
	s_waitcnt lgkmcnt(0)
	ds_write_b32 v161, v4 offset:49152
	global_load_dwordx2 v[4:5], v187, s[74:75]
	global_load_dwordx2 v[36:37], v187, s[76:77]
	global_load_dwordx2 v[6:7], v187, s[78:79]
	global_load_dwordx2 v[44:45], v187, s[80:81]
	global_load_dwordx2 v[38:39], v187, s[82:83]
	s_nop 0
	v_cndmask_b32_e64 v122, 0, 1, s[92:93]
	v_cmp_ne_u32_e64 s[44:45], 1, v122
	s_andn2_b64 vcc, exec, s[92:93]
	s_cbranch_vccnz .LBB0_187
	s_add_i32 s4, s37, -14
	s_cmp_ge_i32 s36, s4
	s_cbranch_scc0 .LBB0_203
.LBB0_187:
	s_waitcnt vmcnt(38)
	s_waitcnt vmcnt(36)
	v_fma_mix_f32 v188, v41, v2, v92 op_sel:[0,0,0] op_sel_hi:[1,0,0]
	v_fma_mix_f32 v189, v41, v3, v93 op_sel:[1,0,0] op_sel_hi:[1,0,0]
	v_fma_mix_f32 v190, v40, v0, v94 op_sel:[0,0,0] op_sel_hi:[1,0,0]
	v_fma_mix_f32 v191, v40, v1, v95 op_sel:[1,0,0] op_sel_hi:[1,0,0]
	v_fma_mix_f32 v192, v53, v188, 0 op_sel:[0,0,0] op_sel_hi:[1,0,0]
	v_fma_mix_f32 v193, v53, v189, 0 op_sel:[1,0,0] op_sel_hi:[1,0,0]
	v_fma_mix_f32 v194, v52, v190, 0 op_sel:[0,0,0] op_sel_hi:[1,0,0]
	v_fma_mix_f32 v195, v52, v191, 0 op_sel:[1,0,0] op_sel_hi:[1,0,0]
	s_and_b32 s4, s23, 9
	s_mulk_i32 s4, 0xc00
	s_add_i32 s4, s4, 16
	v_pk_mul_f16 v122, v40, v10
	v_add3_u32 v40, s4, v113, v128
	v_pk_mul_f16 v123, v41, v11
	v_cvt_pk_f16_f32 v125, v192, v193
	v_cvt_pk_f16_f32 v124, v194, v195
	ds_write_b128 v40, v[8:11]
	ds_write_b128 v40, v[122:125] offset:1024
	v_add_u32_e32 v8, s4, v111
	s_or_b32 s4, s37, 2
	s_waitcnt vmcnt(35)
	v_add_u32_e32 v185, v8, v186
	ds_write_b64 v185, v[46:47] offset:2048
	v_mov_b32_e32 v8, s4
	s_min_u32 s4, s37, 0x1036
	s_lshl_b32 s4, s4, 2
	s_cmp_gt_u32 s37, 54
	s_cselect_b32 s5, 0xffffff24, 36
	s_cselect_b32 s23, s10, s33
	s_cselect_b32 s92, s46, 0xfc
	s_add_i32 s93, s4, s5
	s_sub_i32 s92, s92, s93
	s_and_b64 s[4:5], s[42:43], exec
	s_cselect_b32 s4, s93, s92
	s_add_i32 s4, s4, s23
	s_ashr_i32 s5, s4, 31
	s_lshl_b64 s[4:5], s[4:5], 11
	v_add_u32_e32 v187, s4, v119
	s_waitcnt lgkmcnt(0)
	ds_write_b32 v161, v8 offset:49152
	global_load_dwordx2 v[8:9], v187, s[74:75]
	global_load_dwordx2 v[40:41], v187, s[76:77]
	global_load_dwordx2 v[10:11], v187, s[78:79]
	global_load_dwordx2 v[52:53], v187, s[80:81]
	global_load_dwordx2 v[46:47], v187, s[82:83]
	s_nop 0
	s_and_b64 vcc, exec, s[44:45]
	s_cbranch_vccnz .LBB0_189
	s_add_i32 s4, s37, -13
	s_cmp_ge_i32 s36, s4
	s_cbranch_scc0 .LBB0_206
.LBB0_189:
	s_waitcnt vmcnt(38)
	s_waitcnt vmcnt(36)
	v_fma_mix_f32 v188, v49, v2, v92 op_sel:[0,0,0] op_sel_hi:[1,0,0]
	v_fma_mix_f32 v189, v49, v3, v93 op_sel:[1,0,0] op_sel_hi:[1,0,0]
	v_fma_mix_f32 v190, v48, v0, v94 op_sel:[0,0,0] op_sel_hi:[1,0,0]
	v_fma_mix_f32 v191, v48, v1, v95 op_sel:[1,0,0] op_sel_hi:[1,0,0]
	v_fma_mix_f32 v192, v61, v188, 0 op_sel:[0,0,0] op_sel_hi:[1,0,0]
	v_fma_mix_f32 v193, v61, v189, 0 op_sel:[1,0,0] op_sel_hi:[1,0,0]
	v_fma_mix_f32 v194, v60, v190, 0 op_sel:[0,0,0] op_sel_hi:[1,0,0]
	v_fma_mix_f32 v195, v60, v191, 0 op_sel:[1,0,0] op_sel_hi:[1,0,0]
	s_or_b32 s4, s37, 3
	v_pk_mul_f16 v123, v49, v15
	v_pk_mul_f16 v122, v48, v14
	v_cvt_pk_f16_f32 v125, v192, v193
	v_cvt_pk_f16_f32 v124, v194, v195
	ds_write_b128 v120, v[12:15] offset:6144
	ds_write_b128 v120, v[122:125] offset:7168
	s_waitcnt vmcnt(35)
	v_add_u32_e32 v185, v121, v186
	ds_write_b64 v185, v[54:55] offset:8192
	v_mov_b32_e32 v12, s4
	s_min_u32 s4, s37, 0x1035
	s_lshl_b32 s4, s4, 2
	s_cmp_gt_u32 s37, 53
	s_cselect_b32 s5, 0xffffff28, 40
	s_cselect_b32 s23, s10, s33
	s_cselect_b32 s92, s46, 0xfc
	s_add_i32 s93, s4, s5
	s_sub_i32 s92, s92, s93
	s_and_b64 s[4:5], s[42:43], exec
	s_cselect_b32 s4, s93, s92
	s_add_i32 s4, s4, s23
	s_ashr_i32 s5, s4, 31
	s_lshl_b64 s[4:5], s[4:5], 11
	v_add_u32_e32 v187, s4, v119
	s_waitcnt lgkmcnt(0)
	ds_write_b32 v161, v12 offset:49152
	global_load_dwordx2 v[12:13], v187, s[74:75]
	global_load_dwordx2 v[48:49], v187, s[76:77]
	global_load_dwordx2 v[14:15], v187, s[78:79]
	global_load_dwordx2 v[60:61], v187, s[80:81]
	global_load_dwordx2 v[54:55], v187, s[82:83]
	s_nop 0
	s_and_b64 vcc, exec, s[44:45]
	s_cbranch_vccnz .LBB0_191
	s_add_i32 s4, s37, -12
	s_cmp_ge_i32 s36, s4
	s_cbranch_scc0 .LBB0_209
.LBB0_191:
	s_waitcnt vmcnt(38)
	s_waitcnt vmcnt(36)
	v_fma_mix_f32 v188, v57, v2, v92 op_sel:[0,0,0] op_sel_hi:[1,0,0]
	v_fma_mix_f32 v189, v57, v3, v93 op_sel:[1,0,0] op_sel_hi:[1,0,0]
	v_fma_mix_f32 v190, v56, v0, v94 op_sel:[0,0,0] op_sel_hi:[1,0,0]
	v_fma_mix_f32 v191, v56, v1, v95 op_sel:[1,0,0] op_sel_hi:[1,0,0]
	v_fma_mix_f32 v192, v67, v188, 0 op_sel:[0,0,0] op_sel_hi:[1,0,0]
	v_fma_mix_f32 v193, v67, v189, 0 op_sel:[1,0,0] op_sel_hi:[1,0,0]
	v_fma_mix_f32 v194, v66, v190, 0 op_sel:[0,0,0] op_sel_hi:[1,0,0]
	v_fma_mix_f32 v195, v66, v191, 0 op_sel:[1,0,0] op_sel_hi:[1,0,0]
	s_or_b32 s4, s37, 4
	v_pk_mul_f16 v123, v57, v19
	v_pk_mul_f16 v122, v56, v18
	v_cvt_pk_f16_f32 v125, v192, v193
	v_cvt_pk_f16_f32 v124, v194, v195
	ds_write_b128 v120, v[16:19] offset:9216
	ds_write_b128 v120, v[122:125] offset:10240
	s_waitcnt vmcnt(35)
	v_add_u32_e32 v185, v121, v186
	ds_write_b64 v185, v[62:63] offset:11264
	v_mov_b32_e32 v16, s4
	s_min_u32 s4, s37, 0x1034
	s_lshl_b32 s4, s4, 2
	s_cmp_gt_u32 s37, 52
	s_cselect_b32 s5, 0xffffff2c, 44
	s_cselect_b32 s23, s10, s33
	s_cselect_b32 s92, s46, 0xfc
	s_add_i32 s93, s4, s5
	s_sub_i32 s92, s92, s93
	s_and_b64 s[4:5], s[42:43], exec
	s_cselect_b32 s4, s93, s92
	s_add_i32 s4, s4, s23
	s_ashr_i32 s5, s4, 31
	s_lshl_b64 s[4:5], s[4:5], 11
	v_add_u32_e32 v187, s4, v119
	s_waitcnt lgkmcnt(0)
	ds_write_b32 v161, v16 offset:49152
	global_load_dwordx2 v[16:17], v187, s[74:75]
	global_load_dwordx2 v[56:57], v187, s[76:77]
	global_load_dwordx2 v[18:19], v187, s[78:79]
	global_load_dwordx2 v[66:67], v187, s[80:81]
	global_load_dwordx2 v[62:63], v187, s[82:83]
	s_nop 0
	s_and_b64 vcc, exec, s[44:45]
	s_cbranch_vccnz .LBB0_193
	s_add_i32 s4, s37, -11
	s_cmp_ge_i32 s36, s4
	s_cbranch_scc0 .LBB0_212
.LBB0_193:
	s_waitcnt vmcnt(38)
	s_waitcnt vmcnt(36)
	v_fma_mix_f32 v188, v65, v2, v92 op_sel:[0,0,0] op_sel_hi:[1,0,0]
	v_fma_mix_f32 v189, v65, v3, v93 op_sel:[1,0,0] op_sel_hi:[1,0,0]
	v_fma_mix_f32 v190, v64, v0, v94 op_sel:[0,0,0] op_sel_hi:[1,0,0]
	v_fma_mix_f32 v191, v64, v1, v95 op_sel:[1,0,0] op_sel_hi:[1,0,0]
	v_fma_mix_f32 v192, v77, v188, 0 op_sel:[0,0,0] op_sel_hi:[1,0,0]
	v_fma_mix_f32 v193, v77, v189, 0 op_sel:[1,0,0] op_sel_hi:[1,0,0]
	v_fma_mix_f32 v194, v76, v190, 0 op_sel:[0,0,0] op_sel_hi:[1,0,0]
	v_fma_mix_f32 v195, v76, v191, 0 op_sel:[1,0,0] op_sel_hi:[1,0,0]
	s_or_b32 s4, s37, 5
	v_pk_mul_f16 v123, v65, v23
	v_pk_mul_f16 v122, v64, v22
	v_cvt_pk_f16_f32 v125, v192, v193
	v_cvt_pk_f16_f32 v124, v194, v195
	ds_write_b128 v120, v[20:23] offset:12288
	ds_write_b128 v120, v[122:125] offset:13312
	s_waitcnt vmcnt(35)
	v_add_u32_e32 v185, v121, v186
	ds_write_b64 v185, v[70:71] offset:14336
	v_mov_b32_e32 v20, s4
	s_min_u32 s4, s37, 0x1033
	s_lshl_b32 s4, s4, 2
	s_cmp_gt_u32 s37, 51
	s_cselect_b32 s5, 0xffffff30, 48
	s_cselect_b32 s23, s10, s33
	s_cselect_b32 s92, s46, 0xfc
	s_add_i32 s93, s4, s5
	s_sub_i32 s92, s92, s93
	s_and_b64 s[4:5], s[42:43], exec
	s_cselect_b32 s4, s93, s92
	s_add_i32 s4, s4, s23
	s_ashr_i32 s5, s4, 31
	s_lshl_b64 s[4:5], s[4:5], 11
	v_add_u32_e32 v187, s4, v119
	s_waitcnt lgkmcnt(0)
	ds_write_b32 v161, v20 offset:49152
	global_load_dwordx2 v[20:21], v187, s[74:75]
	global_load_dwordx2 v[64:65], v187, s[76:77]
	global_load_dwordx2 v[22:23], v187, s[78:79]
	global_load_dwordx2 v[76:77], v187, s[80:81]
	global_load_dwordx2 v[70:71], v187, s[82:83]
	s_nop 0
	s_and_b64 vcc, exec, s[44:45]
	s_cbranch_vccnz .LBB0_195
	s_add_i32 s4, s37, -10
	s_cmp_ge_i32 s36, s4
	s_cbranch_scc0 .LBB0_215
.LBB0_195:
	s_waitcnt vmcnt(38)
	s_waitcnt vmcnt(36)
	v_fma_mix_f32 v188, v73, v2, v92 op_sel:[0,0,0] op_sel_hi:[1,0,0]
	v_fma_mix_f32 v189, v73, v3, v93 op_sel:[1,0,0] op_sel_hi:[1,0,0]
	v_fma_mix_f32 v190, v72, v0, v94 op_sel:[0,0,0] op_sel_hi:[1,0,0]
	v_fma_mix_f32 v191, v72, v1, v95 op_sel:[1,0,0] op_sel_hi:[1,0,0]
	v_fma_mix_f32 v192, v85, v188, 0 op_sel:[0,0,0] op_sel_hi:[1,0,0]
	v_fma_mix_f32 v193, v85, v189, 0 op_sel:[1,0,0] op_sel_hi:[1,0,0]
	v_fma_mix_f32 v194, v84, v190, 0 op_sel:[0,0,0] op_sel_hi:[1,0,0]
	v_fma_mix_f32 v195, v84, v191, 0 op_sel:[1,0,0] op_sel_hi:[1,0,0]
	s_or_b32 s4, s37, 6
	v_pk_mul_f16 v123, v73, v27
	v_pk_mul_f16 v122, v72, v26
	v_cvt_pk_f16_f32 v125, v192, v193
	v_cvt_pk_f16_f32 v124, v194, v195
	ds_write_b128 v120, v[24:27] offset:15360
	ds_write_b128 v120, v[122:125] offset:16384
	s_waitcnt vmcnt(35)
	v_add_u32_e32 v185, v121, v186
	ds_write_b64 v185, v[78:79] offset:17408
	v_mov_b32_e32 v24, s4
	s_min_u32 s4, s37, 0x1032
	s_lshl_b32 s4, s4, 2
	s_cmp_gt_u32 s37, 50
	s_cselect_b32 s5, 0xffffff34, 52
	s_cselect_b32 s23, s10, s33
	s_cselect_b32 s92, s46, 0xfc
	s_add_i32 s93, s4, s5
	s_sub_i32 s92, s92, s93
	s_and_b64 s[4:5], s[42:43], exec
	s_cselect_b32 s4, s93, s92
	s_add_i32 s4, s4, s23
	s_ashr_i32 s5, s4, 31
	s_lshl_b64 s[4:5], s[4:5], 11
	v_add_u32_e32 v187, s4, v119
	s_waitcnt lgkmcnt(0)
	ds_write_b32 v161, v24 offset:49152
	global_load_dwordx2 v[24:25], v187, s[74:75]
	global_load_dwordx2 v[72:73], v187, s[76:77]
	global_load_dwordx2 v[26:27], v187, s[78:79]
	global_load_dwordx2 v[84:85], v187, s[80:81]
	global_load_dwordx2 v[78:79], v187, s[82:83]
	s_nop 0
	s_and_b64 vcc, exec, s[44:45]
	s_cbranch_vccnz .LBB0_197
	s_add_i32 s4, s37, -9
	s_cmp_ge_i32 s36, s4
	s_cbranch_scc0 .LBB0_218
.LBB0_197:
	s_waitcnt vmcnt(38)
	s_waitcnt vmcnt(36)
	v_fma_mix_f32 v188, v83, v2, v92 op_sel:[0,0,0] op_sel_hi:[1,0,0]
	v_fma_mix_f32 v189, v83, v3, v93 op_sel:[1,0,0] op_sel_hi:[1,0,0]
	v_fma_mix_f32 v190, v82, v0, v94 op_sel:[0,0,0] op_sel_hi:[1,0,0]
	v_fma_mix_f32 v191, v82, v1, v95 op_sel:[1,0,0] op_sel_hi:[1,0,0]
	v_fma_mix_f32 v192, v99, v188, 0 op_sel:[0,0,0] op_sel_hi:[1,0,0]
	v_fma_mix_f32 v193, v99, v189, 0 op_sel:[1,0,0] op_sel_hi:[1,0,0]
	v_fma_mix_f32 v194, v98, v190, 0 op_sel:[0,0,0] op_sel_hi:[1,0,0]
	v_fma_mix_f32 v195, v98, v191, 0 op_sel:[1,0,0] op_sel_hi:[1,0,0]
	s_or_b32 s4, s37, 7
	v_pk_mul_f16 v123, v83, v31
	v_pk_mul_f16 v122, v82, v30
	v_cvt_pk_f16_f32 v125, v192, v193
	v_cvt_pk_f16_f32 v124, v194, v195
	ds_write_b128 v120, v[28:31] offset:18432
	ds_write_b128 v120, v[122:125] offset:19456
	s_waitcnt vmcnt(35)
	v_add_u32_e32 v185, v121, v186
	ds_write_b64 v185, v[88:89] offset:20480
	v_mov_b32_e32 v28, s4
	s_min_u32 s4, s37, 0x1031
	s_lshl_b32 s4, s4, 2
	s_cmp_gt_u32 s37, 49
	s_cselect_b32 s5, 0xffffff38, 56
	s_cselect_b32 s23, s10, s33
	s_cselect_b32 s92, s46, 0xfc
	s_add_i32 s93, s4, s5
	s_sub_i32 s92, s92, s93
	s_and_b64 s[4:5], s[42:43], exec
	s_cselect_b32 s4, s93, s92
	s_add_i32 s4, s4, s23
	s_ashr_i32 s5, s4, 31
	s_lshl_b64 s[4:5], s[4:5], 11
	v_add_u32_e32 v187, s4, v119
	s_waitcnt lgkmcnt(0)
	ds_write_b32 v161, v28 offset:49152
	global_load_dwordx2 v[28:29], v187, s[74:75]
	global_load_dwordx2 v[82:83], v187, s[76:77]
	global_load_dwordx2 v[30:31], v187, s[78:79]
	global_load_dwordx2 v[98:99], v187, s[80:81]
	global_load_dwordx2 v[88:89], v187, s[82:83]
	s_nop 0
	s_and_b64 vcc, exec, s[44:45]
	s_cbranch_vccnz .LBB0_182
	s_add_i32 s4, s37, -8
	s_cmp_ge_i32 s36, s4
	s_cbranch_scc0 .LBB0_221
	s_branch .LBB0_182
